# K-loops of FFN-up/SSD-in/FFN-down: LDS-DMA issues spread over the MFMA stream (after M2,M6,M10,M14)
# baseline (speedup 1.0000x reference)
.LBB0_1161:
	s_and_b32 s21, s20, 0x18000
	v_add_u32_e32 v128, s21, v203
	s_add_i32 s21, s20, 0xfffe8000
	s_and_b32 s21, s21, 0x18000
	v_or_b32_e32 v222, s21, v202
	v_add_u32_e32 v223, s21, v199
	s_waitcnt vmcnt(8) lgkmcnt(0)
	s_barrier
	v_add_u32_e32 v180, v222, v200
	v_add_u32_e32 v224, v223, v200
	ds_read_b128 v[176:179], v180 offset:16384
	ds_read_b128 v[180:183], v180 offset:18432
	ds_read_b128 v[184:187], v224
	ds_read_b128 v[188:191], v224 offset:2048
	ds_read_b128 v[192:195], v224 offset:4096
	ds_read_b128 v[240:243], v224 offset:6144
	s_waitcnt lgkmcnt(9)
	v_mfma_f32_32x32x16_bf16 v[112:127], v[150:153], v[142:145], v[112:127]
	v_mfma_f32_32x32x16_bf16 v[96:111], v[150:153], v[130:133], v[96:111]
	v_readfirstlane_b32 s21, v128
	s_mov_b32 m0, s21
	s_nop 0
	global_load_lds_dwordx4 v[172:173], off
	s_waitcnt lgkmcnt(8)
	v_mfma_f32_32x32x16_bf16 v[80:95], v[146:149], v[142:145], v[80:95]
	v_mfma_f32_32x32x16_bf16 v[64:79], v[146:149], v[130:133], v[64:79]
	s_waitcnt lgkmcnt(7)
	v_mfma_f32_32x32x16_bf16 v[48:63], v[138:141], v[142:145], v[48:63]
	v_mfma_f32_32x32x16_bf16 v[32:47], v[138:141], v[130:133], v[32:47]
	s_add_i32 s22, s21, 0x2000
	v_lshl_add_u64 v[150:151], v[172:173], 0, s[26:27]
	s_mov_b32 m0, s22
	s_nop 0
	global_load_lds_dwordx4 v[150:151], off
	s_waitcnt lgkmcnt(6)
	v_mfma_f32_32x32x16_bf16 v[16:31], v[134:137], v[142:145], v[16:31]
	v_mfma_f32_32x32x16_bf16 v[0:15], v[134:137], v[130:133], v[0:15]
	v_add_u32_e32 v128, v222, v201
	ds_read_b128 v[142:145], v128 offset:16384
	ds_read_b128 v[130:133], v128 offset:18432
	v_add_u32_e32 v128, v223, v201
	ds_read_b128 v[150:153], v128
	ds_read_b128 v[146:149], v128 offset:2048
	ds_read_b128 v[138:141], v128 offset:4096
	ds_read_b128 v[134:137], v128 offset:6144
	s_waitcnt lgkmcnt(9)
	v_mfma_f32_32x32x16_bf16 v[112:127], v[184:187], v[176:179], v[112:127]
	s_add_i32 s22, s21, 0x6000
	s_addk_i32 s21, 0x4000
	v_mfma_f32_32x32x16_bf16 v[96:111], v[184:187], v[180:183], v[96:111]
	s_mov_b32 m0, s21
	s_nop 0
	global_load_lds_dwordx4 v[174:175], off
	v_lshl_add_u64 v[224:225], v[174:175], 0, s[26:27]
	s_waitcnt lgkmcnt(8)
	v_mfma_f32_32x32x16_bf16 v[80:95], v[188:191], v[176:179], v[80:95]
	v_mfma_f32_32x32x16_bf16 v[64:79], v[188:191], v[180:183], v[64:79]
	s_waitcnt lgkmcnt(7)
	v_mfma_f32_32x32x16_bf16 v[48:63], v[192:195], v[176:179], v[48:63]
	v_mfma_f32_32x32x16_bf16 v[32:47], v[192:195], v[180:183], v[32:47]
	s_mov_b32 m0, s22
	s_nop 0
	global_load_lds_dwordx4 v[224:225], off
	s_waitcnt lgkmcnt(6)
	v_mfma_f32_32x32x16_bf16 v[16:31], v[240:243], v[176:179], v[16:31]
	s_add_i32 s20, s20, 0x8000
	v_lshl_add_u64 v[172:173], v[172:173], 0, 64
	v_lshl_add_u64 v[174:175], v[174:175], 0, 64
	s_cmp_eq_u32 s20, 0x100000
	v_mfma_f32_32x32x16_bf16 v[0:15], v[240:243], v[180:183], v[0:15]
	s_cbranch_scc0 .LBB0_1161
	s_waitcnt vmcnt(8) lgkmcnt(0)
	s_barrier
	v_add_u32_e32 v128, v202, v200
	ds_read_b128 v[172:175], v128 offset:49152
	ds_read_b128 v[176:179], v128 offset:51200
	v_add_u32_e32 v128, v199, v200
	ds_read_b128 v[180:183], v128 offset:32768
	ds_read_b128 v[184:187], v128 offset:34816
	ds_read_b128 v[188:191], v128 offset:36864
	ds_read_b128 v[192:195], v128 offset:38912
	s_waitcnt lgkmcnt(9)
	v_mfma_f32_32x32x16_bf16 v[112:127], v[150:153], v[142:145], v[112:127]
	v_mfma_f32_32x32x16_bf16 v[96:111], v[150:153], v[130:133], v[96:111]
	s_waitcnt lgkmcnt(8)
	v_mfma_f32_32x32x16_bf16 v[80:95], v[146:149], v[142:145], v[80:95]
	v_mfma_f32_32x32x16_bf16 v[64:79], v[146:149], v[130:133], v[64:79]
	s_waitcnt lgkmcnt(7)
	v_mfma_f32_32x32x16_bf16 v[48:63], v[138:141], v[142:145], v[48:63]
	v_mfma_f32_32x32x16_bf16 v[32:47], v[138:141], v[130:133], v[32:47]
	s_waitcnt lgkmcnt(6)
	v_mfma_f32_32x32x16_bf16 v[16:31], v[134:137], v[142:145], v[16:31]
	v_mfma_f32_32x32x16_bf16 v[0:15], v[134:137], v[130:133], v[0:15]
	v_add_u32_e32 v128, v202, v201
	ds_read_b128 v[130:133], v128 offset:49152
	ds_read_b128 v[134:137], v128 offset:51200
	v_add_u32_e32 v128, v199, v201
	ds_read_b128 v[138:141], v128 offset:32768
	ds_read_b128 v[142:145], v128 offset:34816
	ds_read_b128 v[146:149], v128 offset:36864
	ds_read_b128 v[150:153], v128 offset:38912
	s_waitcnt lgkmcnt(9)
	v_mfma_f32_32x32x16_bf16 v[112:127], v[180:183], v[172:175], v[112:127]
	v_mfma_f32_32x32x16_bf16 v[96:111], v[180:183], v[176:179], v[96:111]
	s_waitcnt lgkmcnt(8)
	v_mfma_f32_32x32x16_bf16 v[80:95], v[184:187], v[172:175], v[80:95]
	v_mfma_f32_32x32x16_bf16 v[64:79], v[184:187], v[176:179], v[64:79]
	s_waitcnt lgkmcnt(7)
	v_mfma_f32_32x32x16_bf16 v[48:63], v[188:191], v[172:175], v[48:63]
	v_mfma_f32_32x32x16_bf16 v[32:47], v[188:191], v[176:179], v[32:47]
	s_waitcnt vmcnt(4) lgkmcnt(0)
	s_barrier
	v_add_u32_e32 v128, v236, v200
	s_waitcnt lgkmcnt(6)
	v_mfma_f32_32x32x16_bf16 v[16:31], v[192:195], v[172:175], v[16:31]
	v_mfma_f32_32x32x16_bf16 v[0:15], v[192:195], v[176:179], v[0:15]
	ds_read_b128 v[172:175], v128 offset:16384
	ds_read_b128 v[176:179], v128 offset:18432
	v_add_u32_e32 v128, v237, v200
	ds_read_b128 v[180:183], v128
	ds_read_b128 v[184:187], v128 offset:2048
	ds_read_b128 v[188:191], v128 offset:4096
	ds_read_b128 v[192:195], v128 offset:6144
	s_waitcnt lgkmcnt(9)
	v_mfma_f32_32x32x16_bf16 v[112:127], v[138:141], v[130:133], v[112:127]
	v_mfma_f32_32x32x16_bf16 v[96:111], v[138:141], v[134:137], v[96:111]
	s_waitcnt lgkmcnt(8)
	v_mfma_f32_32x32x16_bf16 v[80:95], v[142:145], v[130:133], v[80:95]
	v_mfma_f32_32x32x16_bf16 v[64:79], v[142:145], v[134:137], v[64:79]
	s_waitcnt lgkmcnt(7)
	v_mfma_f32_32x32x16_bf16 v[48:63], v[146:149], v[130:133], v[48:63]
	v_mfma_f32_32x32x16_bf16 v[32:47], v[146:149], v[134:137], v[32:47]
	s_waitcnt lgkmcnt(6)
	v_mfma_f32_32x32x16_bf16 v[16:31], v[150:153], v[130:133], v[16:31]
	v_mfma_f32_32x32x16_bf16 v[0:15], v[150:153], v[134:137], v[0:15]
	v_add_u32_e32 v128, v236, v201
	ds_read_b128 v[130:133], v128 offset:16384
	ds_read_b128 v[134:137], v128 offset:18432
	v_add_u32_e32 v128, v237, v201
	ds_read_b128 v[138:141], v128
	ds_read_b128 v[142:145], v128 offset:2048
	ds_read_b128 v[146:149], v128 offset:4096
	ds_read_b128 v[150:153], v128 offset:6144
	s_waitcnt lgkmcnt(9)
	v_mfma_f32_32x32x16_bf16 v[112:127], v[180:183], v[172:175], v[112:127]
	v_mfma_f32_32x32x16_bf16 v[96:111], v[180:183], v[176:179], v[96:111]
	s_waitcnt lgkmcnt(8)
	v_mfma_f32_32x32x16_bf16 v[80:95], v[184:187], v[172:175], v[80:95]
	v_mfma_f32_32x32x16_bf16 v[64:79], v[184:187], v[176:179], v[64:79]
	s_waitcnt lgkmcnt(7)
	v_mfma_f32_32x32x16_bf16 v[48:63], v[188:191], v[172:175], v[48:63]
	v_mfma_f32_32x32x16_bf16 v[32:47], v[188:191], v[176:179], v[32:47]
	s_waitcnt vmcnt(0) lgkmcnt(0)
	s_barrier
	v_add_u32_e32 v128, v234, v200
	s_waitcnt lgkmcnt(6)
	v_mfma_f32_32x32x16_bf16 v[16:31], v[192:195], v[172:175], v[16:31]
	v_mfma_f32_32x32x16_bf16 v[0:15], v[192:195], v[176:179], v[0:15]
	ds_read_b128 v[172:175], v128 offset:16384
	ds_read_b128 v[176:179], v128 offset:18432
	v_add_u32_e32 v128, v235, v200
	ds_read_b128 v[180:183], v128
	ds_read_b128 v[184:187], v128 offset:2048
	ds_read_b128 v[188:191], v128 offset:4096
	ds_read_b128 v[192:195], v128 offset:6144
	s_waitcnt lgkmcnt(9)
	v_mfma_f32_32x32x16_bf16 v[112:127], v[138:141], v[130:133], v[112:127]
	v_mfma_f32_32x32x16_bf16 v[96:111], v[138:141], v[134:137], v[96:111]
	s_waitcnt lgkmcnt(8)
	v_mfma_f32_32x32x16_bf16 v[80:95], v[142:145], v[130:133], v[80:95]
	v_mfma_f32_32x32x16_bf16 v[64:79], v[142:145], v[134:137], v[64:79]
	s_waitcnt lgkmcnt(7)
	v_mfma_f32_32x32x16_bf16 v[48:63], v[146:149], v[130:133], v[48:63]
	v_mfma_f32_32x32x16_bf16 v[32:47], v[146:149], v[134:137], v[32:47]
	s_waitcnt lgkmcnt(6)
	v_mfma_f32_32x32x16_bf16 v[16:31], v[150:153], v[130:133], v[16:31]
	v_mfma_f32_32x32x16_bf16 v[0:15], v[150:153], v[134:137], v[0:15]
	v_add_u32_e32 v128, v234, v201
	ds_read_b128 v[130:133], v128 offset:16384
	ds_read_b128 v[136:139], v128 offset:18432
	v_add_u32_e32 v128, v235, v201
	ds_read_b128 v[140:143], v128
	ds_read_b128 v[144:147], v128 offset:2048
	ds_read_b128 v[148:151], v128 offset:4096
	ds_read_b128 v[240:243], v128 offset:6144
	s_waitcnt lgkmcnt(9)
	v_mfma_f32_32x32x16_bf16 v[112:127], v[180:183], v[172:175], v[112:127]
	v_mfma_f32_32x32x16_bf16 v[96:111], v[180:183], v[176:179], v[96:111]
	s_waitcnt lgkmcnt(8)
	v_mfma_f32_32x32x16_bf16 v[80:95], v[184:187], v[172:175], v[80:95]
	v_mfma_f32_32x32x16_bf16 v[64:79], v[184:187], v[176:179], v[64:79]
	s_waitcnt lgkmcnt(7)
	v_mfma_f32_32x32x16_bf16 v[48:63], v[188:191], v[172:175], v[48:63]
	v_mfma_f32_32x32x16_bf16 v[32:47], v[188:191], v[176:179], v[32:47]
	s_waitcnt lgkmcnt(6)
	v_mfma_f32_32x32x16_bf16 v[16:31], v[192:195], v[172:175], v[16:31]
	v_or_b32_e32 v134, s1, v196
	s_movk_i32 s1, 0x1840
	v_cmp_gt_i32_e32 vcc, s1, v134
	v_mfma_f32_32x32x16_bf16 v[0:15], v[192:195], v[176:179], v[0:15]
	s_waitcnt lgkmcnt(3)
	v_mfma_f32_32x32x16_bf16 v[112:127], v[140:143], v[130:133], v[112:127]
	v_mfma_f32_32x32x16_bf16 v[96:111], v[140:143], v[136:139], v[96:111]
	s_waitcnt lgkmcnt(2)
	v_mfma_f32_32x32x16_bf16 v[80:95], v[144:147], v[130:133], v[80:95]
	v_mfma_f32_32x32x16_bf16 v[64:79], v[144:147], v[136:139], v[64:79]
	s_waitcnt lgkmcnt(1)
	v_mfma_f32_32x32x16_bf16 v[48:63], v[148:151], v[130:133], v[48:63]
	v_mfma_f32_32x32x16_bf16 v[32:47], v[148:151], v[136:139], v[32:47]
	s_waitcnt lgkmcnt(0)
	v_mfma_f32_32x32x16_bf16 v[16:31], v[240:243], v[130:133], v[16:31]
	v_mfma_f32_32x32x16_bf16 v[0:15], v[240:243], v[136:139], v[0:15]
	s_and_saveexec_b64 s[20:21], vcc
	s_cbranch_execz .LBB0_1159
	v_add_u32_e32 v239, s0, v159
	s_movk_i32 s0, 0x7ff
	v_cmp_lt_i32_e32 vcc, s0, v134
	s_and_saveexec_b64 s[0:1], vcc
	s_xor_b64 s[22:23], exec, s[0:1]
	s_cbranch_execz .LBB0_1816
	s_cmpk_lt_u32 s24, 0x1800
	v_or_b32_e32 v130, v134, v197
	s_mov_b64 s[0:1], -1
	s_cbranch_scc0 .LBB0_1302
	v_add_u32_e32 v128, 0xfffff800, v130
	v_lshlrev_b64 v[132:133], 2, v[128:129]
	v_lshl_add_u64 v[134:135], s[16:17], 0, v[132:133]
	v_add_co_u32_e32 v136, vcc, 0x4000, v134
	v_lshl_add_u64 v[132:133], s[18:19], 0, v[132:133]
	s_nop 0
	v_addc_co_u32_e32 v137, vcc, 0, v135, vcc
	v_add_co_u32_e32 v138, vcc, 0x8000, v134
	v_mov_b32_e32 v131, v113
	s_nop 0
	v_addc_co_u32_e32 v139, vcc, 0, v135, vcc
	global_load_dword v188, v[134:135], off
	s_nop 0
	global_load_dword v134, v[136:137], off
	global_load_dword v186, v[138:139], off
	global_load_dword v190, v[132:133], off
	v_ashrrev_i32_e32 v132, 7, v239
	v_ashrrev_i32_e32 v133, 31, v132
	v_lshlrev_b64 v[136:137], 15, v[132:133]
	v_lshl_add_u64 v[178:179], s[2:3], 0, v[136:137]
	v_lshl_add_u64 v[136:137], v[128:129], 1, v[178:179]
	s_and_saveexec_b64 s[0:1], s[6:7]
	s_xor_b64 s[0:1], exec, s[0:1]
	s_cbranch_execz .LBB0_1167
	v_add_co_u32_e32 v138, vcc, 0x4000, v136
	v_cvt_pk_bf16_f32 v131, v30, s0
	s_nop 0
	v_addc_co_u32_e32 v139, vcc, 0, v137, vcc
	global_store_short v[138:139], v131, off
	v_mov_b32_e32 v131, v31

.LBB0_2340:
	s_and_b32 s19, s18, 0x18000
	v_add_u32_e32 v187, s19, v180
	s_add_i32 s19, s18, 0xfffe8000
	s_and_b32 s19, s19, 0x18000
	v_or_b32_e32 v212, s19, v179
	v_add_u32_e32 v213, s19, v176
	s_waitcnt vmcnt(8) lgkmcnt(0)
	s_barrier
	v_add_u32_e32 v192, v212, v177
	v_add_u32_e32 v208, v213, v177
	ds_read_b128 v[188:191], v192 offset:16384
	ds_read_b128 v[192:195], v192 offset:18432
	ds_read_b128 v[196:199], v208
	ds_read_b128 v[200:203], v208 offset:2048
	ds_read_b128 v[204:207], v208 offset:4096
	ds_read_b128 v[208:211], v208 offset:6144
	s_waitcnt lgkmcnt(9)
	v_mfma_f32_32x32x16_bf16 v[112:127], v[150:153], v[142:145], v[112:127]
	v_mfma_f32_32x32x16_bf16 v[96:111], v[150:153], v[130:133], v[96:111]
	v_readfirstlane_b32 s19, v187
	s_mov_b32 m0, s19
	s_nop 0
	global_load_lds_dwordx4 v[170:171], off
	s_waitcnt lgkmcnt(8)
	v_mfma_f32_32x32x16_bf16 v[80:95], v[146:149], v[142:145], v[80:95]
	v_mfma_f32_32x32x16_bf16 v[64:79], v[146:149], v[130:133], v[64:79]
	s_waitcnt lgkmcnt(7)
	v_mfma_f32_32x32x16_bf16 v[48:63], v[138:141], v[142:145], v[48:63]
	v_mfma_f32_32x32x16_bf16 v[32:47], v[138:141], v[130:133], v[32:47]
	s_add_i32 s20, s19, 0x2000
	v_lshl_add_u64 v[150:151], v[170:171], 0, s[34:35]
	s_mov_b32 m0, s20
	s_nop 0
	global_load_lds_dwordx4 v[150:151], off
	s_waitcnt lgkmcnt(6)
	v_mfma_f32_32x32x16_bf16 v[16:31], v[134:137], v[142:145], v[16:31]
	v_mfma_f32_32x32x16_bf16 v[0:15], v[134:137], v[130:133], v[0:15]
	v_add_u32_e32 v130, v212, v178
	v_add_u32_e32 v134, v213, v178
	ds_read_b128 v[142:145], v130 offset:16384
	ds_read_b128 v[130:133], v130 offset:18432
	ds_read_b128 v[150:153], v134
	ds_read_b128 v[146:149], v134 offset:2048
	ds_read_b128 v[138:141], v134 offset:4096
	ds_read_b128 v[134:137], v134 offset:6144
	s_waitcnt lgkmcnt(9)
	v_mfma_f32_32x32x16_bf16 v[112:127], v[196:199], v[188:191], v[112:127]
	s_add_i32 s20, s19, 0x6000
	s_addk_i32 s19, 0x4000
	v_mfma_f32_32x32x16_bf16 v[96:111], v[196:199], v[192:195], v[96:111]
	s_mov_b32 m0, s19
	s_nop 0
	global_load_lds_dwordx4 v[172:173], off
	v_lshl_add_u64 v[212:213], v[172:173], 0, s[34:35]
	s_waitcnt lgkmcnt(8)
	v_mfma_f32_32x32x16_bf16 v[80:95], v[200:203], v[188:191], v[80:95]
	v_mfma_f32_32x32x16_bf16 v[64:79], v[200:203], v[192:195], v[64:79]
	s_waitcnt lgkmcnt(7)
	v_mfma_f32_32x32x16_bf16 v[48:63], v[204:207], v[188:191], v[48:63]
	v_mfma_f32_32x32x16_bf16 v[32:47], v[204:207], v[192:195], v[32:47]
	s_mov_b32 m0, s20
	s_nop 0
	global_load_lds_dwordx4 v[212:213], off
	s_waitcnt lgkmcnt(6)
	v_mfma_f32_32x32x16_bf16 v[16:31], v[208:211], v[188:191], v[16:31]
	s_add_i32 s18, s18, 0x8000
	v_lshl_add_u64 v[170:171], v[170:171], 0, 64
	v_lshl_add_u64 v[172:173], v[172:173], 0, 64
	s_cmp_eq_u32 s18, 0x100000
	v_mfma_f32_32x32x16_bf16 v[0:15], v[208:211], v[192:195], v[0:15]
	s_cbranch_scc0 .LBB0_2340
	s_waitcnt vmcnt(8) lgkmcnt(0)
	s_barrier
	v_add_u32_e32 v187, v179, v177
	ds_read_b128 v[170:173], v187 offset:49152
	ds_read_b128 v[188:191], v187 offset:51200
	v_add_u32_e32 v187, v176, v177
	ds_read_b128 v[192:195], v187 offset:32768
	ds_read_b128 v[196:199], v187 offset:34816
	ds_read_b128 v[200:203], v187 offset:36864
	ds_read_b128 v[204:207], v187 offset:38912
	s_waitcnt lgkmcnt(9)
	v_mfma_f32_32x32x16_bf16 v[112:127], v[150:153], v[142:145], v[112:127]
	v_mfma_f32_32x32x16_bf16 v[96:111], v[150:153], v[130:133], v[96:111]
	s_waitcnt lgkmcnt(8)
	v_mfma_f32_32x32x16_bf16 v[80:95], v[146:149], v[142:145], v[80:95]
	v_mfma_f32_32x32x16_bf16 v[64:79], v[146:149], v[130:133], v[64:79]
	s_waitcnt lgkmcnt(7)
	v_mfma_f32_32x32x16_bf16 v[48:63], v[138:141], v[142:145], v[48:63]
	v_mfma_f32_32x32x16_bf16 v[32:47], v[138:141], v[130:133], v[32:47]
	s_waitcnt lgkmcnt(6)
	v_mfma_f32_32x32x16_bf16 v[16:31], v[134:137], v[142:145], v[16:31]
	v_mfma_f32_32x32x16_bf16 v[0:15], v[134:137], v[130:133], v[0:15]
	v_add_u32_e32 v134, v179, v178
	v_add_u32_e32 v150, v176, v178
	ds_read_b128 v[130:133], v134 offset:49152
	ds_read_b128 v[134:137], v134 offset:51200
	ds_read_b128 v[138:141], v150 offset:32768
	ds_read_b128 v[142:145], v150 offset:34816
	ds_read_b128 v[146:149], v150 offset:36864
	ds_read_b128 v[150:153], v150 offset:38912
	s_waitcnt lgkmcnt(9)
	v_mfma_f32_32x32x16_bf16 v[112:127], v[192:195], v[170:173], v[112:127]
	v_mfma_f32_32x32x16_bf16 v[96:111], v[192:195], v[188:191], v[96:111]
	s_waitcnt lgkmcnt(8)
	v_mfma_f32_32x32x16_bf16 v[80:95], v[196:199], v[170:173], v[80:95]
	v_mfma_f32_32x32x16_bf16 v[64:79], v[196:199], v[188:191], v[64:79]
	s_waitcnt lgkmcnt(7)
	v_mfma_f32_32x32x16_bf16 v[48:63], v[200:203], v[170:173], v[48:63]
	v_mfma_f32_32x32x16_bf16 v[32:47], v[200:203], v[188:191], v[32:47]
	s_waitcnt vmcnt(4) lgkmcnt(0)
	s_barrier
	v_add_u32_e32 v187, v184, v177
	s_waitcnt lgkmcnt(6)
	v_mfma_f32_32x32x16_bf16 v[16:31], v[204:207], v[170:173], v[16:31]
	v_mfma_f32_32x32x16_bf16 v[0:15], v[204:207], v[188:191], v[0:15]
	ds_read_b128 v[170:173], v187 offset:16384
	ds_read_b128 v[188:191], v187 offset:18432
	v_add_u32_e32 v187, v185, v177
	ds_read_b128 v[192:195], v187
	ds_read_b128 v[196:199], v187 offset:2048
	ds_read_b128 v[200:203], v187 offset:4096
	ds_read_b128 v[204:207], v187 offset:6144
	s_waitcnt lgkmcnt(9)
	v_mfma_f32_32x32x16_bf16 v[112:127], v[138:141], v[130:133], v[112:127]
	v_mfma_f32_32x32x16_bf16 v[96:111], v[138:141], v[134:137], v[96:111]
	s_waitcnt lgkmcnt(8)
	v_mfma_f32_32x32x16_bf16 v[80:95], v[142:145], v[130:133], v[80:95]
	v_mfma_f32_32x32x16_bf16 v[64:79], v[142:145], v[134:137], v[64:79]
	s_waitcnt lgkmcnt(7)
	v_mfma_f32_32x32x16_bf16 v[48:63], v[146:149], v[130:133], v[48:63]
	v_mfma_f32_32x32x16_bf16 v[32:47], v[146:149], v[134:137], v[32:47]
	s_waitcnt lgkmcnt(6)
	v_mfma_f32_32x32x16_bf16 v[16:31], v[150:153], v[130:133], v[16:31]
	v_mfma_f32_32x32x16_bf16 v[0:15], v[150:153], v[134:137], v[0:15]
	v_add_u32_e32 v134, v184, v178
	v_add_u32_e32 v150, v185, v178
	ds_read_b128 v[130:133], v134 offset:16384
	ds_read_b128 v[134:137], v134 offset:18432
	ds_read_b128 v[138:141], v150
	ds_read_b128 v[142:145], v150 offset:2048
	ds_read_b128 v[146:149], v150 offset:4096
	ds_read_b128 v[150:153], v150 offset:6144
	s_waitcnt lgkmcnt(9)
	v_mfma_f32_32x32x16_bf16 v[112:127], v[192:195], v[170:173], v[112:127]
	v_mfma_f32_32x32x16_bf16 v[96:111], v[192:195], v[188:191], v[96:111]
	s_waitcnt lgkmcnt(8)
	v_mfma_f32_32x32x16_bf16 v[80:95], v[196:199], v[170:173], v[80:95]
	v_mfma_f32_32x32x16_bf16 v[64:79], v[196:199], v[188:191], v[64:79]
	s_waitcnt lgkmcnt(7)
	v_mfma_f32_32x32x16_bf16 v[48:63], v[200:203], v[170:173], v[48:63]
	v_mfma_f32_32x32x16_bf16 v[32:47], v[200:203], v[188:191], v[32:47]
	s_waitcnt vmcnt(0) lgkmcnt(0)
	s_barrier
	v_add_u32_e32 v187, v182, v177
	s_waitcnt lgkmcnt(6)
	v_mfma_f32_32x32x16_bf16 v[16:31], v[204:207], v[170:173], v[16:31]
	v_mfma_f32_32x32x16_bf16 v[0:15], v[204:207], v[188:191], v[0:15]
	ds_read_b128 v[170:173], v187 offset:16384
	ds_read_b128 v[188:191], v187 offset:18432
	v_add_u32_e32 v187, v183, v177
	ds_read_b128 v[192:195], v187
	ds_read_b128 v[196:199], v187 offset:2048
	ds_read_b128 v[200:203], v187 offset:4096
	ds_read_b128 v[204:207], v187 offset:6144
	s_waitcnt lgkmcnt(9)
	v_mfma_f32_32x32x16_bf16 v[112:127], v[138:141], v[130:133], v[112:127]
	v_mfma_f32_32x32x16_bf16 v[96:111], v[138:141], v[134:137], v[96:111]
	s_waitcnt lgkmcnt(8)
	v_mfma_f32_32x32x16_bf16 v[80:95], v[142:145], v[130:133], v[80:95]
	v_mfma_f32_32x32x16_bf16 v[64:79], v[142:145], v[134:137], v[64:79]
	s_waitcnt lgkmcnt(7)
	v_mfma_f32_32x32x16_bf16 v[48:63], v[146:149], v[130:133], v[48:63]
	v_mfma_f32_32x32x16_bf16 v[32:47], v[146:149], v[134:137], v[32:47]
	s_waitcnt lgkmcnt(6)
	v_mfma_f32_32x32x16_bf16 v[16:31], v[150:153], v[130:133], v[16:31]
	v_mfma_f32_32x32x16_bf16 v[0:15], v[150:153], v[134:137], v[0:15]
	v_add_u32_e32 v134, v182, v178
	v_add_u32_e32 v150, v183, v178
	ds_read_b128 v[130:133], v134 offset:16384
	ds_read_b128 v[134:137], v134 offset:18432
	ds_read_b128 v[138:141], v150
	ds_read_b128 v[142:145], v150 offset:2048
	ds_read_b128 v[146:149], v150 offset:4096
	ds_read_b128 v[150:153], v150 offset:6144
	s_waitcnt lgkmcnt(9)
	v_mfma_f32_32x32x16_bf16 v[112:127], v[192:195], v[170:173], v[112:127]
	v_mfma_f32_32x32x16_bf16 v[96:111], v[192:195], v[188:191], v[96:111]
	s_waitcnt lgkmcnt(8)
	v_mfma_f32_32x32x16_bf16 v[80:95], v[196:199], v[170:173], v[80:95]
	v_mfma_f32_32x32x16_bf16 v[64:79], v[196:199], v[188:191], v[64:79]
	s_waitcnt lgkmcnt(7)
	v_mfma_f32_32x32x16_bf16 v[48:63], v[200:203], v[170:173], v[48:63]
	v_mfma_f32_32x32x16_bf16 v[32:47], v[200:203], v[188:191], v[32:47]
	s_waitcnt lgkmcnt(6)
	v_mfma_f32_32x32x16_bf16 v[16:31], v[204:207], v[170:173], v[16:31]
	v_mfma_f32_32x32x16_bf16 v[0:15], v[204:207], v[188:191], v[0:15]
	s_waitcnt lgkmcnt(3)
	v_mfma_f32_32x32x16_bf16 v[112:127], v[138:141], v[130:133], v[112:127]
	s_waitcnt lgkmcnt(2)
	v_mfma_f32_32x32x16_bf16 v[80:95], v[142:145], v[130:133], v[80:95]
	s_waitcnt lgkmcnt(1)
	v_mfma_f32_32x32x16_bf16 v[48:63], v[146:149], v[130:133], v[48:63]
	s_waitcnt lgkmcnt(0)
	v_mfma_f32_32x32x16_bf16 v[16:31], v[150:153], v[130:133], v[16:31]
	v_or_b32_e32 v132, s12, v174
	v_ashrrev_i32_e32 v130, 1, v132
	v_or_b32_e32 v130, v130, v154
	v_ashrrev_i32_e32 v131, 31, v130
	s_movk_i32 s12, 0x5000
	v_mfma_f32_32x32x16_bf16 v[96:111], v[138:141], v[134:137], v[96:111]
	v_mfma_f32_32x32x16_bf16 v[64:79], v[142:145], v[134:137], v[64:79]
	v_add_u32_e32 v142, s13, v155
	s_mov_b32 s13, 0xb000
	v_ashrrev_i32_e32 v133, 7, v142
	v_mfma_f32_32x32x16_bf16 v[32:47], v[146:149], v[134:137], v[32:47]
	v_mfma_f32_32x32x16_bf16 v[0:15], v[150:153], v[134:137], v[0:15]
	v_lshl_add_u64 v[134:135], v[130:131], 2, s[10:11]
	v_add_co_u32_e32 v138, vcc, s12, v134
	s_mov_b32 s12, 0x8000
	s_nop 0
	v_addc_co_u32_e32 v139, vcc, 0, v135, vcc
	global_load_dword v137, v[138:139], off offset:2048
	v_add_co_u32_e32 v138, vcc, s13, v134
	global_load_dword v136, v[134:135], off
	s_nop 0
	v_addc_co_u32_e32 v139, vcc, 0, v135, vcc
	v_add_co_u32_e32 v140, vcc, s47, v134
	global_load_dword v139, v[138:139], off
	s_nop 0
	v_addc_co_u32_e32 v141, vcc, 0, v135, vcc
	global_load_dword v138, v[140:141], off offset:3072
	v_add_co_u32_e32 v140, vcc, s12, v134
	s_mov_b32 s12, 0xd000
	s_nop 0
	v_addc_co_u32_e32 v141, vcc, 0, v135, vcc
	v_add_co_u32_e32 v134, vcc, s12, v134
	global_load_dword v140, v[140:141], off offset:1024
	s_nop 0
	v_addc_co_u32_e32 v135, vcc, 0, v135, vcc
	global_load_dword v141, v[134:135], off offset:3072
	v_mov_b64_e32 v[134:135], s[8:9]
	v_mad_i64_i32 v[134:135], s[12:13], v133, s13, v[134:135]
	v_ashrrev_i32_e32 v133, 31, v132
	v_lshl_add_u64 v[132:133], v[132:133], 1, v[134:135]
	v_lshl_add_u64 v[132:133], v[132:133], 0, v[128:129]
	s_and_saveexec_b64 s[12:13], s[2:3]
	s_xor_b64 s[12:13], exec, s[12:13]
	s_cbranch_execz .LBB0_2343
	v_add_co_u32_e32 v134, vcc, 0x5000, v132
	v_cvt_pk_bf16_f32 v143, v30, s0
	s_nop 0
	v_addc_co_u32_e32 v135, vcc, 0, v133, vcc
	global_store_short v[134:135], v143, off offset:2048
	v_cvt_pk_bf16_f32 v143, v14, s0
	global_store_short v[134:135], v143, off offset:2112
	v_add_co_u32_e32 v134, vcc, 0x8000, v132
	v_cvt_pk_bf16_f32 v143, v31, s0
	s_nop 0
	v_addc_co_u32_e32 v135, vcc, 0, v133, vcc
	global_store_short v[134:135], v143, off offset:1024

.LBB0_2551:
	s_and_b32 s7, s5, 0x18000
	v_add_u32_e32 v222, s7, v180
	s_add_i32 s7, s5, 0xfffe8000
	s_and_b32 s7, s7, 0x18000
	v_or_b32_e32 v223, s7, v179
	v_add_u32_e32 v233, s7, v176
	s_waitcnt vmcnt(8) lgkmcnt(0)
	s_barrier
	v_add_u32_e32 v206, v223, v177
	v_add_u32_e32 v234, v233, v177
	ds_read_b128 v[202:205], v206 offset:16384
	ds_read_b128 v[206:209], v206 offset:18432
	ds_read_b128 v[210:213], v234
	ds_read_b128 v[214:217], v234 offset:2048
	ds_read_b128 v[224:227], v234 offset:4096
	ds_read_b128 v[234:237], v234 offset:6144
	s_waitcnt lgkmcnt(9)
	v_mfma_f32_32x32x16_bf16 v[112:127], v[150:153], v[142:145], v[112:127]
	v_mfma_f32_32x32x16_bf16 v[96:111], v[150:153], v[130:133], v[96:111]
	v_readfirstlane_b32 s7, v222
	s_mov_b32 m0, s7
	s_nop 0
	global_load_lds_dwordx4 v[170:171], off
	s_waitcnt lgkmcnt(8)
	v_mfma_f32_32x32x16_bf16 v[80:95], v[146:149], v[142:145], v[80:95]
	v_mfma_f32_32x32x16_bf16 v[64:79], v[146:149], v[130:133], v[64:79]
	s_waitcnt lgkmcnt(7)
	v_mfma_f32_32x32x16_bf16 v[48:63], v[138:141], v[142:145], v[48:63]
	v_mfma_f32_32x32x16_bf16 v[32:47], v[138:141], v[130:133], v[32:47]
	s_add_i32 s8, s7, 0x2000
	v_lshl_add_u64 v[150:151], v[170:171], 0, s[10:11]
	s_mov_b32 m0, s8
	s_nop 0
	global_load_lds_dwordx4 v[150:151], off
	s_waitcnt lgkmcnt(6)
	v_mfma_f32_32x32x16_bf16 v[16:31], v[134:137], v[142:145], v[16:31]
	v_mfma_f32_32x32x16_bf16 v[0:15], v[134:137], v[130:133], v[0:15]
	v_add_u32_e32 v130, v223, v178
	v_add_u32_e32 v134, v233, v178
	ds_read_b128 v[142:145], v130 offset:16384
	ds_read_b128 v[130:133], v130 offset:18432
	ds_read_b128 v[150:153], v134
	ds_read_b128 v[146:149], v134 offset:2048
	ds_read_b128 v[138:141], v134 offset:4096
	ds_read_b128 v[134:137], v134 offset:6144
	s_waitcnt lgkmcnt(9)
	v_mfma_f32_32x32x16_bf16 v[112:127], v[210:213], v[202:205], v[112:127]
	s_add_i32 s8, s7, 0x6000
	s_addk_i32 s7, 0x4000
	v_mfma_f32_32x32x16_bf16 v[96:111], v[210:213], v[206:209], v[96:111]
	s_mov_b32 m0, s7
	s_nop 0
	global_load_lds_dwordx4 v[172:173], off
	v_lshl_add_u64 v[222:223], v[172:173], 0, s[10:11]
	s_waitcnt lgkmcnt(8)
	v_mfma_f32_32x32x16_bf16 v[80:95], v[214:217], v[202:205], v[80:95]
	v_mfma_f32_32x32x16_bf16 v[64:79], v[214:217], v[206:209], v[64:79]
	s_waitcnt lgkmcnt(7)
	v_mfma_f32_32x32x16_bf16 v[48:63], v[224:227], v[202:205], v[48:63]
	v_mfma_f32_32x32x16_bf16 v[32:47], v[224:227], v[206:209], v[32:47]
	s_mov_b32 m0, s8
	s_nop 0
	global_load_lds_dwordx4 v[222:223], off
	s_waitcnt lgkmcnt(6)
	v_mfma_f32_32x32x16_bf16 v[16:31], v[234:237], v[202:205], v[16:31]
	s_add_i32 s5, s5, 0x8000
	v_lshl_add_u64 v[170:171], v[170:171], 0, 64
	v_lshl_add_u64 v[172:173], v[172:173], 0, 64
	s_cmp_eq_u32 s5, 0x2c0000
	v_mfma_f32_32x32x16_bf16 v[0:15], v[234:237], v[206:209], v[0:15]
	s_cbranch_scc0 .LBB0_2551
	s_waitcnt vmcnt(8) lgkmcnt(0)
	s_barrier
	v_add_u32_e32 v202, v179, v177
	v_add_u32_e32 v222, v176, v177
	ds_read_b128 v[170:173], v202 offset:49152
	ds_read_b128 v[202:205], v202 offset:51200
	ds_read_b128 v[206:209], v222 offset:32768
	ds_read_b128 v[210:213], v222 offset:34816
	ds_read_b128 v[214:217], v222 offset:36864
	ds_read_b128 v[224:227], v222 offset:38912
	s_waitcnt lgkmcnt(9)
	v_mfma_f32_32x32x16_bf16 v[112:127], v[150:153], v[142:145], v[112:127]
	v_mfma_f32_32x32x16_bf16 v[96:111], v[150:153], v[130:133], v[96:111]
	s_waitcnt lgkmcnt(8)
	v_mfma_f32_32x32x16_bf16 v[80:95], v[146:149], v[142:145], v[80:95]
	v_mfma_f32_32x32x16_bf16 v[64:79], v[146:149], v[130:133], v[64:79]
	s_waitcnt lgkmcnt(7)
	v_mfma_f32_32x32x16_bf16 v[48:63], v[138:141], v[142:145], v[48:63]
	v_mfma_f32_32x32x16_bf16 v[32:47], v[138:141], v[130:133], v[32:47]
	s_waitcnt lgkmcnt(6)
	v_mfma_f32_32x32x16_bf16 v[16:31], v[134:137], v[142:145], v[16:31]
	v_mfma_f32_32x32x16_bf16 v[0:15], v[134:137], v[130:133], v[0:15]
	v_add_u32_e32 v134, v179, v178
	v_add_u32_e32 v150, v176, v178
	ds_read_b128 v[130:133], v134 offset:49152
	ds_read_b128 v[134:137], v134 offset:51200
	ds_read_b128 v[138:141], v150 offset:32768
	ds_read_b128 v[142:145], v150 offset:34816
	ds_read_b128 v[146:149], v150 offset:36864
	ds_read_b128 v[150:153], v150 offset:38912
	s_waitcnt lgkmcnt(9)
	v_mfma_f32_32x32x16_bf16 v[112:127], v[206:209], v[170:173], v[112:127]
	v_mfma_f32_32x32x16_bf16 v[96:111], v[206:209], v[202:205], v[96:111]
	s_waitcnt lgkmcnt(8)
	v_mfma_f32_32x32x16_bf16 v[80:95], v[210:213], v[170:173], v[80:95]
	v_mfma_f32_32x32x16_bf16 v[64:79], v[210:213], v[202:205], v[64:79]
	s_waitcnt lgkmcnt(7)
	v_mfma_f32_32x32x16_bf16 v[48:63], v[214:217], v[170:173], v[48:63]
	v_mfma_f32_32x32x16_bf16 v[32:47], v[214:217], v[202:205], v[32:47]
	s_waitcnt lgkmcnt(6)
	v_mfma_f32_32x32x16_bf16 v[0:15], v[224:227], v[202:205], v[0:15]
	s_waitcnt vmcnt(4) lgkmcnt(0)
	s_barrier
	v_add_u32_e32 v202, v199, v177
	v_add_u32_e32 v222, v200, v177
	v_mfma_f32_32x32x16_bf16 v[16:31], v[224:227], v[170:173], v[16:31]
	ds_read_b128 v[170:173], v202 offset:16384
	ds_read_b128 v[202:205], v202 offset:18432
	ds_read_b128 v[206:209], v222
	ds_read_b128 v[210:213], v222 offset:2048
	ds_read_b128 v[214:217], v222 offset:4096
	ds_read_b128 v[224:227], v222 offset:6144
	s_waitcnt lgkmcnt(9)
	v_mfma_f32_32x32x16_bf16 v[112:127], v[138:141], v[130:133], v[112:127]
	v_mfma_f32_32x32x16_bf16 v[96:111], v[138:141], v[134:137], v[96:111]
	s_waitcnt lgkmcnt(8)
	v_mfma_f32_32x32x16_bf16 v[80:95], v[142:145], v[130:133], v[80:95]
	v_mfma_f32_32x32x16_bf16 v[64:79], v[142:145], v[134:137], v[64:79]
	s_waitcnt lgkmcnt(7)
	v_mfma_f32_32x32x16_bf16 v[48:63], v[146:149], v[130:133], v[48:63]
	v_mfma_f32_32x32x16_bf16 v[32:47], v[146:149], v[134:137], v[32:47]
	s_waitcnt lgkmcnt(6)
	v_mfma_f32_32x32x16_bf16 v[16:31], v[150:153], v[130:133], v[16:31]
	v_mfma_f32_32x32x16_bf16 v[0:15], v[150:153], v[134:137], v[0:15]
	v_add_u32_e32 v134, v199, v178
	v_add_u32_e32 v150, v200, v178
	ds_read_b128 v[130:133], v134 offset:16384
	ds_read_b128 v[134:137], v134 offset:18432
	ds_read_b128 v[138:141], v150
	ds_read_b128 v[142:145], v150 offset:2048
	ds_read_b128 v[146:149], v150 offset:4096
	ds_read_b128 v[150:153], v150 offset:6144
	s_waitcnt lgkmcnt(9)
	v_mfma_f32_32x32x16_bf16 v[112:127], v[206:209], v[170:173], v[112:127]
	v_mfma_f32_32x32x16_bf16 v[96:111], v[206:209], v[202:205], v[96:111]
	s_waitcnt lgkmcnt(8)
	v_mfma_f32_32x32x16_bf16 v[80:95], v[210:213], v[170:173], v[80:95]
	v_mfma_f32_32x32x16_bf16 v[64:79], v[210:213], v[202:205], v[64:79]
	s_waitcnt lgkmcnt(7)
	v_mfma_f32_32x32x16_bf16 v[48:63], v[214:217], v[170:173], v[48:63]
	v_mfma_f32_32x32x16_bf16 v[32:47], v[214:217], v[202:205], v[32:47]
	s_waitcnt lgkmcnt(6)
	v_mfma_f32_32x32x16_bf16 v[0:15], v[224:227], v[202:205], v[0:15]
	s_waitcnt vmcnt(0) lgkmcnt(0)
	s_barrier
	v_add_u32_e32 v202, v197, v177
	v_add_u32_e32 v222, v198, v177
	v_mfma_f32_32x32x16_bf16 v[16:31], v[224:227], v[170:173], v[16:31]
	ds_read_b128 v[170:173], v202 offset:16384
	ds_read_b128 v[202:205], v202 offset:18432
	ds_read_b128 v[206:209], v222
	ds_read_b128 v[210:213], v222 offset:2048
	ds_read_b128 v[214:217], v222 offset:4096
	ds_read_b128 v[224:227], v222 offset:6144
	s_waitcnt lgkmcnt(9)
	v_mfma_f32_32x32x16_bf16 v[112:127], v[138:141], v[130:133], v[112:127]
	v_mfma_f32_32x32x16_bf16 v[96:111], v[138:141], v[134:137], v[96:111]
	s_waitcnt lgkmcnt(8)
	v_mfma_f32_32x32x16_bf16 v[80:95], v[142:145], v[130:133], v[80:95]
	v_mfma_f32_32x32x16_bf16 v[64:79], v[142:145], v[134:137], v[64:79]
	s_waitcnt lgkmcnt(7)
	v_mfma_f32_32x32x16_bf16 v[48:63], v[146:149], v[130:133], v[48:63]
	v_mfma_f32_32x32x16_bf16 v[32:47], v[146:149], v[134:137], v[32:47]
	s_waitcnt lgkmcnt(6)
	v_mfma_f32_32x32x16_bf16 v[16:31], v[150:153], v[130:133], v[16:31]
	v_mfma_f32_32x32x16_bf16 v[0:15], v[150:153], v[134:137], v[0:15]
	v_add_u32_e32 v134, v197, v178
	v_add_u32_e32 v150, v198, v178
	ds_read_b128 v[130:133], v134 offset:16384
	ds_read_b128 v[134:137], v134 offset:18432
	ds_read_b128 v[138:141], v150
	ds_read_b128 v[142:145], v150 offset:2048
	ds_read_b128 v[146:149], v150 offset:4096
	ds_read_b128 v[150:153], v150 offset:6144
	s_waitcnt lgkmcnt(9)
	v_mfma_f32_32x32x16_bf16 v[112:127], v[206:209], v[170:173], v[112:127]
	v_mfma_f32_32x32x16_bf16 v[96:111], v[206:209], v[202:205], v[96:111]
	s_waitcnt lgkmcnt(8)
	v_mfma_f32_32x32x16_bf16 v[80:95], v[210:213], v[170:173], v[80:95]
	v_mfma_f32_32x32x16_bf16 v[64:79], v[210:213], v[202:205], v[64:79]
	s_waitcnt lgkmcnt(7)
	v_mfma_f32_32x32x16_bf16 v[48:63], v[214:217], v[170:173], v[48:63]
	v_mfma_f32_32x32x16_bf16 v[32:47], v[214:217], v[202:205], v[32:47]
	s_waitcnt lgkmcnt(6)
	v_mfma_f32_32x32x16_bf16 v[16:31], v[224:227], v[170:173], v[16:31]
	s_movk_i32 s7, 0x1600
	v_mfma_f32_32x32x16_bf16 v[0:15], v[224:227], v[202:205], v[0:15]
	s_waitcnt lgkmcnt(3)
	v_mfma_f32_32x32x16_bf16 v[112:127], v[138:141], v[130:133], v[112:127]
	v_mfma_f32_32x32x16_bf16 v[96:111], v[138:141], v[134:137], v[96:111]
	s_nop 10
	v_cvt_pk_bf16_f32 v112, v112, s0
	s_waitcnt lgkmcnt(2)
	v_mfma_f32_32x32x16_bf16 v[80:95], v[142:145], v[130:133], v[80:95]
	v_cvt_pk_bf16_f32 v96, v96, s0
	v_cvt_pk_bf16_f32 v98, v98, s0
	s_waitcnt lgkmcnt(1)
	v_mfma_f32_32x32x16_bf16 v[48:63], v[146:149], v[130:133], v[48:63]
	s_nop 7
	v_cvt_pk_bf16_f32 v80, v80, s0
	s_waitcnt lgkmcnt(0)
	v_mfma_f32_32x32x16_bf16 v[16:31], v[150:153], v[130:133], v[16:31]
	v_add_u32_e32 v132, s3, v128
	v_or_b32_e32 v130, s4, v174
	v_ashrrev_i32_e32 v131, 31, v130
	v_lshl_add_u64 v[130:131], v[130:131], 1, v[158:159]
	v_cvt_pk_bf16_f32 v48, v48, s0
	v_readlane_b32 s3, v252, 7
	s_add_i32 s6, s6, s3
	v_mfma_f32_32x32x16_bf16 v[64:79], v[142:145], v[134:137], v[64:79]
	s_nop 3
	v_cvt_pk_bf16_f32 v16, v16, s0
	v_mfma_f32_32x32x16_bf16 v[32:47], v[146:149], v[134:137], v[32:47]
	s_nop 5
	v_cvt_pk_bf16_f32 v64, v64, s0
	v_cvt_pk_bf16_f32 v66, v66, s0
	v_mfma_f32_32x32x16_bf16 v[0:15], v[150:153], v[134:137], v[0:15]
	v_or_b32_e32 v134, v132, v181
	v_ashrrev_i32_e32 v135, 31, v134
	v_lshlrev_b64 v[134:135], 11, v[134:135]
	v_lshl_add_u64 v[134:135], v[130:131], 0, v[134:135]
	global_store_short v[134:135], v112, off
	global_store_short v[134:135], v96, off offset:64
	v_or_b32_e32 v134, v132, v182
	v_ashrrev_i32_e32 v135, 31, v134
	v_lshlrev_b64 v[134:135], 11, v[134:135]
	v_lshl_add_u64 v[134:135], v[130:131], 0, v[134:135]
	v_cvt_pk_bf16_f32 v96, v113, s0
	global_store_short v[134:135], v96, off
	v_cvt_pk_bf16_f32 v96, v97, s0
	global_store_short v[134:135], v96, off offset:64
	v_or_b32_e32 v96, v132, v183
	v_ashrrev_i32_e32 v97, 31, v96
	v_lshlrev_b64 v[96:97], 11, v[96:97]
	v_lshl_add_u64 v[96:97], v[130:131], 0, v[96:97]
	v_cvt_pk_bf16_f32 v112, v114, s0
	global_store_short v[96:97], v112, off
	global_store_short v[96:97], v98, off offset:64
	v_or_b32_e32 v96, v132, v184
	v_ashrrev_i32_e32 v97, 31, v96
	v_lshlrev_b64 v[96:97], 11, v[96:97]
	v_lshl_add_u64 v[96:97], v[130:131], 0, v[96:97]
	v_cvt_pk_bf16_f32 v98, v115, s0
	global_store_short v[96:97], v98, off
	v_cvt_pk_bf16_f32 v98, v99, s0
	global_store_short v[96:97], v98, off offset:64
	v_or_b32_e32 v96, v132, v185
	v_ashrrev_i32_e32 v97, 31, v96
	v_lshlrev_b64 v[96:97], 11, v[96:97]
	v_lshl_add_u64 v[96:97], v[130:131], 0, v[96:97]
	v_cvt_pk_bf16_f32 v98, v116, s0
	global_store_short v[96:97], v98, off
	v_cvt_pk_bf16_f32 v98, v100, s0
	global_store_short v[96:97], v98, off offset:64
	v_or_b32_e32 v96, v132, v186
	v_ashrrev_i32_e32 v97, 31, v96
	v_lshlrev_b64 v[96:97], 11, v[96:97]
	v_lshl_add_u64 v[96:97], v[130:131], 0, v[96:97]
	v_cvt_pk_bf16_f32 v98, v117, s0
	global_store_short v[96:97], v98, off
	v_cvt_pk_bf16_f32 v98, v101, s0
	global_store_short v[96:97], v98, off offset:64
	v_or_b32_e32 v96, v132, v187
	v_ashrrev_i32_e32 v97, 31, v96
	v_lshlrev_b64 v[96:97], 11, v[96:97]
	v_lshl_add_u64 v[96:97], v[130:131], 0, v[96:97]
	v_cvt_pk_bf16_f32 v98, v118, s0
	global_store_short v[96:97], v98, off
	v_cvt_pk_bf16_f32 v98, v102, s0
	global_store_short v[96:97], v98, off offset:64
	v_or_b32_e32 v96, v132, v188
	v_ashrrev_i32_e32 v97, 31, v96
	v_lshlrev_b64 v[96:97], 11, v[96:97]
	v_lshl_add_u64 v[96:97], v[130:131], 0, v[96:97]
	v_cvt_pk_bf16_f32 v98, v119, s0
	global_store_short v[96:97], v98, off
	v_cvt_pk_bf16_f32 v98, v103, s0
	global_store_short v[96:97], v98, off offset:64
	v_or_b32_e32 v96, v132, v189
	v_ashrrev_i32_e32 v97, 31, v96
	v_lshlrev_b64 v[96:97], 11, v[96:97]
	v_lshl_add_u64 v[96:97], v[130:131], 0, v[96:97]
	v_cvt_pk_bf16_f32 v98, v120, s0
	global_store_short v[96:97], v98, off
	v_cvt_pk_bf16_f32 v98, v104, s0
	global_store_short v[96:97], v98, off offset:64
	v_or_b32_e32 v96, v132, v190
	v_ashrrev_i32_e32 v97, 31, v96
	v_lshlrev_b64 v[96:97], 11, v[96:97]
	v_lshl_add_u64 v[96:97], v[130:131], 0, v[96:97]
	v_cvt_pk_bf16_f32 v98, v121, s0
	global_store_short v[96:97], v98, off
	v_cvt_pk_bf16_f32 v98, v105, s0
	global_store_short v[96:97], v98, off offset:64
	v_or_b32_e32 v96, v132, v191
	v_ashrrev_i32_e32 v97, 31, v96
	v_lshlrev_b64 v[96:97], 11, v[96:97]
	v_lshl_add_u64 v[96:97], v[130:131], 0, v[96:97]
	v_cvt_pk_bf16_f32 v98, v122, s0
	global_store_short v[96:97], v98, off
	v_cvt_pk_bf16_f32 v98, v106, s0
	global_store_short v[96:97], v98, off offset:64
	v_or_b32_e32 v96, v132, v192
	v_ashrrev_i32_e32 v97, 31, v96
	v_lshlrev_b64 v[96:97], 11, v[96:97]
	v_lshl_add_u64 v[96:97], v[130:131], 0, v[96:97]
	v_cvt_pk_bf16_f32 v98, v123, s0
	global_store_short v[96:97], v98, off
	v_cvt_pk_bf16_f32 v98, v107, s0
	global_store_short v[96:97], v98, off offset:64
	v_or_b32_e32 v96, v132, v193
	v_ashrrev_i32_e32 v97, 31, v96
	v_lshlrev_b64 v[96:97], 11, v[96:97]
	v_lshl_add_u64 v[96:97], v[130:131], 0, v[96:97]
	v_cvt_pk_bf16_f32 v98, v124, s0
	global_store_short v[96:97], v98, off
	v_cvt_pk_bf16_f32 v98, v108, s0
	global_store_short v[96:97], v98, off offset:64
	v_or_b32_e32 v96, v132, v194
	v_ashrrev_i32_e32 v97, 31, v96
	v_lshlrev_b64 v[96:97], 11, v[96:97]
	v_lshl_add_u64 v[96:97], v[130:131], 0, v[96:97]
	v_cvt_pk_bf16_f32 v98, v125, s0
	global_store_short v[96:97], v98, off
	v_cvt_pk_bf16_f32 v98, v109, s0
	global_store_short v[96:97], v98, off offset:64
	v_or_b32_e32 v96, v132, v195
	v_ashrrev_i32_e32 v97, 31, v96
	v_lshlrev_b64 v[96:97], 11, v[96:97]
	v_lshl_add_u64 v[96:97], v[130:131], 0, v[96:97]
	v_cvt_pk_bf16_f32 v98, v126, s0
	global_store_short v[96:97], v98, off
	v_cvt_pk_bf16_f32 v98, v110, s0
	global_store_short v[96:97], v98, off offset:64
	v_or_b32_e32 v96, v132, v196
	v_ashrrev_i32_e32 v97, 31, v96
	v_lshlrev_b64 v[96:97], 11, v[96:97]
	v_lshl_add_u64 v[96:97], v[130:131], 0, v[96:97]
	v_cvt_pk_bf16_f32 v98, v127, s0
	global_store_short v[96:97], v98, off
	v_cvt_pk_bf16_f32 v98, v111, s0
	global_store_short v[96:97], v98, off offset:64
	v_or_b32_e32 v98, 32, v132
	v_or_b32_e32 v96, v98, v181
	v_ashrrev_i32_e32 v97, 31, v96
	v_lshlrev_b64 v[96:97], 11, v[96:97]
	v_lshl_add_u64 v[96:97], v[130:131], 0, v[96:97]
	global_store_short v[96:97], v80, off
	global_store_short v[96:97], v64, off offset:64
	v_or_b32_e32 v96, v98, v182
	v_ashrrev_i32_e32 v97, 31, v96
	v_lshlrev_b64 v[96:97], 11, v[96:97]
	v_lshl_add_u64 v[96:97], v[130:131], 0, v[96:97]
	v_cvt_pk_bf16_f32 v64, v81, s0
	global_store_short v[96:97], v64, off
	v_cvt_pk_bf16_f32 v64, v65, s0
	global_store_short v[96:97], v64, off offset:64
	v_or_b32_e32 v64, v98, v183
	v_ashrrev_i32_e32 v65, 31, v64
	v_lshlrev_b64 v[64:65], 11, v[64:65]
	v_lshl_add_u64 v[64:65], v[130:131], 0, v[64:65]
	v_cvt_pk_bf16_f32 v80, v82, s0
	global_store_short v[64:65], v80, off
	global_store_short v[64:65], v66, off offset:64
	v_or_b32_e32 v64, v98, v184
	v_ashrrev_i32_e32 v65, 31, v64
	v_lshlrev_b64 v[64:65], 11, v[64:65]
	v_lshl_add_u64 v[64:65], v[130:131], 0, v[64:65]
	v_cvt_pk_bf16_f32 v66, v83, s0
	global_store_short v[64:65], v66, off
	v_cvt_pk_bf16_f32 v66, v67, s0
	global_store_short v[64:65], v66, off offset:64
	v_or_b32_e32 v64, v98, v185
	v_ashrrev_i32_e32 v65, 31, v64
	v_lshlrev_b64 v[64:65], 11, v[64:65]
	v_lshl_add_u64 v[64:65], v[130:131], 0, v[64:65]
	v_cvt_pk_bf16_f32 v66, v84, s0
	global_store_short v[64:65], v66, off
	v_cvt_pk_bf16_f32 v66, v68, s0
	global_store_short v[64:65], v66, off offset:64
	v_or_b32_e32 v64, v98, v186
	v_ashrrev_i32_e32 v65, 31, v64
	v_lshlrev_b64 v[64:65], 11, v[64:65]
	v_lshl_add_u64 v[64:65], v[130:131], 0, v[64:65]
	v_cvt_pk_bf16_f32 v66, v85, s0
	global_store_short v[64:65], v66, off
	v_cvt_pk_bf16_f32 v66, v69, s0
	global_store_short v[64:65], v66, off offset:64
	v_or_b32_e32 v64, v98, v187
	v_ashrrev_i32_e32 v65, 31, v64
	v_lshlrev_b64 v[64:65], 11, v[64:65]
	v_lshl_add_u64 v[64:65], v[130:131], 0, v[64:65]
	v_cvt_pk_bf16_f32 v66, v86, s0
	global_store_short v[64:65], v66, off
	v_cvt_pk_bf16_f32 v66, v70, s0
	global_store_short v[64:65], v66, off offset:64
	v_or_b32_e32 v64, v98, v188
	v_ashrrev_i32_e32 v65, 31, v64
	v_lshlrev_b64 v[64:65], 11, v[64:65]
	v_lshl_add_u64 v[64:65], v[130:131], 0, v[64:65]
	v_cvt_pk_bf16_f32 v66, v87, s0
	global_store_short v[64:65], v66, off
	v_cvt_pk_bf16_f32 v66, v71, s0
	global_store_short v[64:65], v66, off offset:64
	v_or_b32_e32 v64, v98, v189
	v_ashrrev_i32_e32 v65, 31, v64
	v_lshlrev_b64 v[64:65], 11, v[64:65]
	v_lshl_add_u64 v[64:65], v[130:131], 0, v[64:65]
	v_cvt_pk_bf16_f32 v66, v88, s0
	global_store_short v[64:65], v66, off
	v_cvt_pk_bf16_f32 v66, v72, s0
	global_store_short v[64:65], v66, off offset:64
	v_or_b32_e32 v64, v98, v190
	v_ashrrev_i32_e32 v65, 31, v64
	v_lshlrev_b64 v[64:65], 11, v[64:65]
	v_lshl_add_u64 v[64:65], v[130:131], 0, v[64:65]
	v_cvt_pk_bf16_f32 v66, v89, s0
	global_store_short v[64:65], v66, off
	v_cvt_pk_bf16_f32 v66, v73, s0
	global_store_short v[64:65], v66, off offset:64
	v_or_b32_e32 v64, v98, v191
	v_ashrrev_i32_e32 v65, 31, v64
	v_lshlrev_b64 v[64:65], 11, v[64:65]
	v_lshl_add_u64 v[64:65], v[130:131], 0, v[64:65]
	v_cvt_pk_bf16_f32 v66, v90, s0
	global_store_short v[64:65], v66, off
	v_cvt_pk_bf16_f32 v66, v74, s0
	global_store_short v[64:65], v66, off offset:64
	v_or_b32_e32 v64, v98, v192
	v_ashrrev_i32_e32 v65, 31, v64
	v_lshlrev_b64 v[64:65], 11, v[64:65]
	v_lshl_add_u64 v[64:65], v[130:131], 0, v[64:65]
	v_cvt_pk_bf16_f32 v66, v91, s0
	global_store_short v[64:65], v66, off
	v_cvt_pk_bf16_f32 v66, v75, s0
	global_store_short v[64:65], v66, off offset:64
	v_or_b32_e32 v64, v98, v193
	v_ashrrev_i32_e32 v65, 31, v64
	v_lshlrev_b64 v[64:65], 11, v[64:65]
	v_lshl_add_u64 v[64:65], v[130:131], 0, v[64:65]
	v_cvt_pk_bf16_f32 v66, v92, s0
	global_store_short v[64:65], v66, off
	v_cvt_pk_bf16_f32 v66, v76, s0
	global_store_short v[64:65], v66, off offset:64
	v_or_b32_e32 v64, v98, v194
	v_ashrrev_i32_e32 v65, 31, v64
	v_lshlrev_b64 v[64:65], 11, v[64:65]
	v_lshl_add_u64 v[64:65], v[130:131], 0, v[64:65]
	v_cvt_pk_bf16_f32 v66, v93, s0
	global_store_short v[64:65], v66, off
	v_cvt_pk_bf16_f32 v66, v77, s0
	global_store_short v[64:65], v66, off offset:64
	v_or_b32_e32 v64, v98, v195
	v_ashrrev_i32_e32 v65, 31, v64
	v_lshlrev_b64 v[64:65], 11, v[64:65]
	v_lshl_add_u64 v[64:65], v[130:131], 0, v[64:65]
	v_cvt_pk_bf16_f32 v66, v94, s0
	global_store_short v[64:65], v66, off
	v_cvt_pk_bf16_f32 v66, v78, s0
	global_store_short v[64:65], v66, off offset:64
	v_or_b32_e32 v64, v98, v196
	v_ashrrev_i32_e32 v65, 31, v64
	v_lshlrev_b64 v[64:65], 11, v[64:65]
	v_lshl_add_u64 v[64:65], v[130:131], 0, v[64:65]
	v_cvt_pk_bf16_f32 v66, v95, s0
	global_store_short v[64:65], v66, off
	v_cvt_pk_bf16_f32 v66, v79, s0
	global_store_short v[64:65], v66, off offset:64
	v_or_b32_e32 v66, 64, v132
	v_or_b32_e32 v64, v66, v181
	v_ashrrev_i32_e32 v65, 31, v64
	v_lshlrev_b64 v[64:65], 11, v[64:65]
	v_lshl_add_u64 v[64:65], v[130:131], 0, v[64:65]
	v_cvt_pk_bf16_f32 v32, v32, s0
	global_store_short v[64:65], v48, off
	global_store_short v[64:65], v32, off offset:64
	v_or_b32_e32 v64, v66, v182
	v_ashrrev_i32_e32 v65, 31, v64
	v_lshlrev_b64 v[64:65], 11, v[64:65]
	v_lshl_add_u64 v[64:65], v[130:131], 0, v[64:65]
	v_cvt_pk_bf16_f32 v32, v49, s0
	global_store_short v[64:65], v32, off
	v_cvt_pk_bf16_f32 v32, v33, s0
	global_store_short v[64:65], v32, off offset:64
	v_or_b32_e32 v32, v66, v183
	v_ashrrev_i32_e32 v33, 31, v32
	v_lshlrev_b64 v[32:33], 11, v[32:33]
	v_lshl_add_u64 v[32:33], v[130:131], 0, v[32:33]
	v_cvt_pk_bf16_f32 v48, v50, s0
	v_cvt_pk_bf16_f32 v34, v34, s0
	global_store_short v[32:33], v48, off
	global_store_short v[32:33], v34, off offset:64
	v_or_b32_e32 v32, v66, v184
	v_ashrrev_i32_e32 v33, 31, v32
	v_lshlrev_b64 v[32:33], 11, v[32:33]
	v_lshl_add_u64 v[32:33], v[130:131], 0, v[32:33]
	v_cvt_pk_bf16_f32 v34, v51, s0
	global_store_short v[32:33], v34, off
	v_cvt_pk_bf16_f32 v34, v35, s0
	global_store_short v[32:33], v34, off offset:64
	v_or_b32_e32 v32, v66, v185
	v_ashrrev_i32_e32 v33, 31, v32
	v_lshlrev_b64 v[32:33], 11, v[32:33]
	v_lshl_add_u64 v[32:33], v[130:131], 0, v[32:33]
	v_cvt_pk_bf16_f32 v34, v52, s0
	global_store_short v[32:33], v34, off
	v_cvt_pk_bf16_f32 v34, v36, s0
	global_store_short v[32:33], v34, off offset:64
	v_or_b32_e32 v32, v66, v186
	v_ashrrev_i32_e32 v33, 31, v32
	v_lshlrev_b64 v[32:33], 11, v[32:33]
	v_lshl_add_u64 v[32:33], v[130:131], 0, v[32:33]
	v_cvt_pk_bf16_f32 v34, v53, s0
	global_store_short v[32:33], v34, off
	v_cvt_pk_bf16_f32 v34, v37, s0
	global_store_short v[32:33], v34, off offset:64
	v_or_b32_e32 v32, v66, v187
	v_ashrrev_i32_e32 v33, 31, v32
	v_lshlrev_b64 v[32:33], 11, v[32:33]
	v_lshl_add_u64 v[32:33], v[130:131], 0, v[32:33]
	v_cvt_pk_bf16_f32 v34, v54, s0
	global_store_short v[32:33], v34, off
	v_cvt_pk_bf16_f32 v34, v38, s0
	global_store_short v[32:33], v34, off offset:64
	v_or_b32_e32 v32, v66, v188
	v_ashrrev_i32_e32 v33, 31, v32
	v_lshlrev_b64 v[32:33], 11, v[32:33]
	v_lshl_add_u64 v[32:33], v[130:131], 0, v[32:33]
	v_cvt_pk_bf16_f32 v34, v55, s0
	global_store_short v[32:33], v34, off
	v_cvt_pk_bf16_f32 v34, v39, s0
	global_store_short v[32:33], v34, off offset:64
	v_or_b32_e32 v32, v66, v189
	v_ashrrev_i32_e32 v33, 31, v32
	v_lshlrev_b64 v[32:33], 11, v[32:33]
	v_lshl_add_u64 v[32:33], v[130:131], 0, v[32:33]
	v_cvt_pk_bf16_f32 v34, v56, s0
	global_store_short v[32:33], v34, off
	v_cvt_pk_bf16_f32 v34, v40, s0
	global_store_short v[32:33], v34, off offset:64
	v_or_b32_e32 v32, v66, v190
	v_ashrrev_i32_e32 v33, 31, v32
	v_lshlrev_b64 v[32:33], 11, v[32:33]
	v_lshl_add_u64 v[32:33], v[130:131], 0, v[32:33]
	v_cvt_pk_bf16_f32 v34, v57, s0
	global_store_short v[32:33], v34, off
	v_cvt_pk_bf16_f32 v34, v41, s0
	global_store_short v[32:33], v34, off offset:64
	v_or_b32_e32 v32, v66, v191
	v_ashrrev_i32_e32 v33, 31, v32
	v_lshlrev_b64 v[32:33], 11, v[32:33]
	v_lshl_add_u64 v[32:33], v[130:131], 0, v[32:33]
	v_cvt_pk_bf16_f32 v34, v58, s0
	global_store_short v[32:33], v34, off
	v_cvt_pk_bf16_f32 v34, v42, s0
	global_store_short v[32:33], v34, off offset:64
	v_or_b32_e32 v32, v66, v192
	v_ashrrev_i32_e32 v33, 31, v32
	v_lshlrev_b64 v[32:33], 11, v[32:33]
	v_lshl_add_u64 v[32:33], v[130:131], 0, v[32:33]
	v_cvt_pk_bf16_f32 v34, v59, s0
	global_store_short v[32:33], v34, off
	v_cvt_pk_bf16_f32 v34, v43, s0
	global_store_short v[32:33], v34, off offset:64
	v_or_b32_e32 v32, v66, v193
	v_ashrrev_i32_e32 v33, 31, v32
	v_lshlrev_b64 v[32:33], 11, v[32:33]
	v_lshl_add_u64 v[32:33], v[130:131], 0, v[32:33]
	v_cvt_pk_bf16_f32 v34, v60, s0
	global_store_short v[32:33], v34, off
	v_cvt_pk_bf16_f32 v34, v44, s0
	global_store_short v[32:33], v34, off offset:64
	v_or_b32_e32 v32, v66, v194
	v_ashrrev_i32_e32 v33, 31, v32
	v_lshlrev_b64 v[32:33], 11, v[32:33]
	v_lshl_add_u64 v[32:33], v[130:131], 0, v[32:33]
	v_cvt_pk_bf16_f32 v34, v61, s0
	global_store_short v[32:33], v34, off
	v_cvt_pk_bf16_f32 v34, v45, s0
	global_store_short v[32:33], v34, off offset:64
	v_or_b32_e32 v32, v66, v195
	v_ashrrev_i32_e32 v33, 31, v32
	v_lshlrev_b64 v[32:33], 11, v[32:33]
	v_lshl_add_u64 v[32:33], v[130:131], 0, v[32:33]
	v_cvt_pk_bf16_f32 v34, v62, s0
	global_store_short v[32:33], v34, off
	v_cvt_pk_bf16_f32 v34, v46, s0
	global_store_short v[32:33], v34, off offset:64
	v_or_b32_e32 v32, v66, v196
	v_ashrrev_i32_e32 v33, 31, v32
	v_lshlrev_b64 v[32:33], 11, v[32:33]
	v_lshl_add_u64 v[32:33], v[130:131], 0, v[32:33]
	v_cvt_pk_bf16_f32 v34, v63, s0
	global_store_short v[32:33], v34, off
	v_cvt_pk_bf16_f32 v34, v47, s0
	global_store_short v[32:33], v34, off offset:64
	v_or_b32_e32 v34, 0x60, v132
	v_or_b32_e32 v32, v34, v181
	v_ashrrev_i32_e32 v33, 31, v32
	v_lshlrev_b64 v[32:33], 11, v[32:33]
	v_lshl_add_u64 v[32:33], v[130:131], 0, v[32:33]
	v_cvt_pk_bf16_f32 v0, v0, s0
	global_store_short v[32:33], v16, off
	global_store_short v[32:33], v0, off offset:64
	v_or_b32_e32 v32, v34, v182
	v_ashrrev_i32_e32 v33, 31, v32
	v_lshlrev_b64 v[32:33], 11, v[32:33]
	v_lshl_add_u64 v[32:33], v[130:131], 0, v[32:33]
	v_cvt_pk_bf16_f32 v0, v17, s0
	global_store_short v[32:33], v0, off
	v_cvt_pk_bf16_f32 v0, v1, s0
	global_store_short v[32:33], v0, off offset:64
	v_or_b32_e32 v0, v34, v183
	v_ashrrev_i32_e32 v1, 31, v0
	v_lshlrev_b64 v[0:1], 11, v[0:1]
	v_lshl_add_u64 v[0:1], v[130:131], 0, v[0:1]
	v_cvt_pk_bf16_f32 v16, v18, s0
	v_cvt_pk_bf16_f32 v2, v2, s0
	global_store_short v[0:1], v16, off
	global_store_short v[0:1], v2, off offset:64
	v_or_b32_e32 v0, v34, v184
	v_ashrrev_i32_e32 v1, 31, v0
	v_lshlrev_b64 v[0:1], 11, v[0:1]
	v_lshl_add_u64 v[0:1], v[130:131], 0, v[0:1]
	v_cvt_pk_bf16_f32 v2, v19, s0
	global_store_short v[0:1], v2, off
	v_cvt_pk_bf16_f32 v2, v3, s0
	global_store_short v[0:1], v2, off offset:64
	v_or_b32_e32 v0, v34, v185
	v_ashrrev_i32_e32 v1, 31, v0
	v_lshlrev_b64 v[0:1], 11, v[0:1]
	v_lshl_add_u64 v[0:1], v[130:131], 0, v[0:1]
	v_cvt_pk_bf16_f32 v2, v20, s0
	global_store_short v[0:1], v2, off
	v_cvt_pk_bf16_f32 v2, v4, s0
	global_store_short v[0:1], v2, off offset:64
	v_or_b32_e32 v0, v34, v186
	v_ashrrev_i32_e32 v1, 31, v0
	v_lshlrev_b64 v[0:1], 11, v[0:1]
	v_lshl_add_u64 v[0:1], v[130:131], 0, v[0:1]
	v_cvt_pk_bf16_f32 v2, v21, s0
	global_store_short v[0:1], v2, off
	v_cvt_pk_bf16_f32 v2, v5, s0
	global_store_short v[0:1], v2, off offset:64
	v_or_b32_e32 v0, v34, v187
	v_ashrrev_i32_e32 v1, 31, v0
	v_lshlrev_b64 v[0:1], 11, v[0:1]
	v_lshl_add_u64 v[0:1], v[130:131], 0, v[0:1]
	v_cvt_pk_bf16_f32 v2, v22, s0
	global_store_short v[0:1], v2, off
	v_cvt_pk_bf16_f32 v2, v6, s0
	global_store_short v[0:1], v2, off offset:64
	v_or_b32_e32 v0, v34, v188
	v_ashrrev_i32_e32 v1, 31, v0
	v_lshlrev_b64 v[0:1], 11, v[0:1]
	v_lshl_add_u64 v[0:1], v[130:131], 0, v[0:1]
	v_cvt_pk_bf16_f32 v2, v23, s0
	global_store_short v[0:1], v2, off
	v_cvt_pk_bf16_f32 v2, v7, s0
	global_store_short v[0:1], v2, off offset:64
	v_or_b32_e32 v0, v34, v189
	v_ashrrev_i32_e32 v1, 31, v0
	v_lshlrev_b64 v[0:1], 11, v[0:1]
	v_lshl_add_u64 v[0:1], v[130:131], 0, v[0:1]
	v_cvt_pk_bf16_f32 v2, v24, s0
	global_store_short v[0:1], v2, off
	v_cvt_pk_bf16_f32 v2, v8, s0
	global_store_short v[0:1], v2, off offset:64
	v_or_b32_e32 v0, v34, v190
	v_ashrrev_i32_e32 v1, 31, v0
	v_lshlrev_b64 v[0:1], 11, v[0:1]
	v_lshl_add_u64 v[0:1], v[130:131], 0, v[0:1]
	v_cvt_pk_bf16_f32 v2, v25, s0
	global_store_short v[0:1], v2, off
	v_cvt_pk_bf16_f32 v2, v9, s0
	global_store_short v[0:1], v2, off offset:64
	v_or_b32_e32 v0, v34, v191
	v_ashrrev_i32_e32 v1, 31, v0
	v_lshlrev_b64 v[0:1], 11, v[0:1]
	v_lshl_add_u64 v[0:1], v[130:131], 0, v[0:1]
	v_cvt_pk_bf16_f32 v2, v26, s0
	global_store_short v[0:1], v2, off
	v_cvt_pk_bf16_f32 v2, v10, s0
	global_store_short v[0:1], v2, off offset:64
	v_or_b32_e32 v0, v34, v192
	v_ashrrev_i32_e32 v1, 31, v0
	v_lshlrev_b64 v[0:1], 11, v[0:1]
	v_lshl_add_u64 v[0:1], v[130:131], 0, v[0:1]
	v_cvt_pk_bf16_f32 v2, v27, s0
	global_store_short v[0:1], v2, off
	v_cvt_pk_bf16_f32 v2, v11, s0
	global_store_short v[0:1], v2, off offset:64
	v_or_b32_e32 v0, v34, v193
	v_ashrrev_i32_e32 v1, 31, v0
	v_lshlrev_b64 v[0:1], 11, v[0:1]
	v_lshl_add_u64 v[0:1], v[130:131], 0, v[0:1]
	v_cvt_pk_bf16_f32 v2, v28, s0
	global_store_short v[0:1], v2, off
	v_cvt_pk_bf16_f32 v2, v12, s0
	global_store_short v[0:1], v2, off offset:64
	v_or_b32_e32 v0, v34, v194
	v_ashrrev_i32_e32 v1, 31, v0
	v_lshlrev_b64 v[0:1], 11, v[0:1]
	v_lshl_add_u64 v[0:1], v[130:131], 0, v[0:1]
	v_cvt_pk_bf16_f32 v2, v29, s0
	global_store_short v[0:1], v2, off
	v_cvt_pk_bf16_f32 v2, v13, s0
	global_store_short v[0:1], v2, off offset:64
	v_or_b32_e32 v0, v34, v195
	v_ashrrev_i32_e32 v1, 31, v0
	v_lshlrev_b64 v[0:1], 11, v[0:1]
	v_lshl_add_u64 v[0:1], v[130:131], 0, v[0:1]
	v_cvt_pk_bf16_f32 v2, v30, s0
	global_store_short v[0:1], v2, off
	v_cvt_pk_bf16_f32 v2, v14, s0
	global_store_short v[0:1], v2, off offset:64
	v_or_b32_e32 v0, v34, v196
	v_ashrrev_i32_e32 v1, 31, v0
	v_lshlrev_b64 v[0:1], 11, v[0:1]
	v_lshl_add_u64 v[0:1], v[130:131], 0, v[0:1]
	v_cvt_pk_bf16_f32 v2, v31, s0
	global_store_short v[0:1], v2, off
	v_cvt_pk_bf16_f32 v2, v15, s0
	s_add_i32 s0, s0, s3
	v_readlane_b32 s3, v252, 8
	s_add_i32 s2, s2, s3
	s_cmp_gt_i32 s6, 31
	global_store_short v[0:1], v2, off offset:64
	s_cbranch_scc0 .LBB0_2550
